# grid barrier: waiting workgroups poll the top-level generation word directly; per-XCD release hop removed
# speedup vs baseline: 1.0270x; 1.0048x over previous
; __device__ __forceinline__ unsigned xb_ld(unsigned* p)              { return __hip_atomic_load(p, __ATOMIC_RELAXED, __HIP_MEMORY_SCOPE_AGENT); }
; __device__ __forceinline__ unsigned xb_add(unsigned* p, unsigned v) { return __hip_atomic_fetch_add(p, v, __ATOMIC_RELAXED, __HIP_MEMORY_SCOPE_AGENT); }
; #define XB_SPIN(cond, bar) do { unsigned _sp = 0; while (cond) { __builtin_amdgcn_s_sleep(1); \
;     if ((++_sp & 255u) == 0u) { if (xb_ld(&(bar)[XB_TMO])) break; if (_sp > XB_SPIN_CAP) { atomicAdd(&(bar)[XB_TMO], 1u); break; } } } } while (0)
; __device__ __forceinline__ void xcd_barrier(const XcdBarrier& b) {
;     ...
;         const unsigned old = xb_add(&bar[XB_XSUB(b.x)], 1u);
;         const unsigned gen = old / nloc;
;         if (old + 1u == (gen + 1u) * nloc) {
;             __builtin_amdgcn_fence(__ATOMIC_RELEASE, "agent");
;             asm volatile("s_waitcnt vmcnt(0)" ::: "memory");
;             const unsigned og = xb_add(&bar[XB_TOP], 1u);
;             const unsigned tg = og / nx;
;             if (og + 1u == (tg + 1u) * nx) xb_add(&bar[XB_TOPGEN], 1u);
;             else XB_SPIN(xb_ld(&bar[XB_TOPGEN]) == tg, bar);
;             __builtin_amdgcn_fence(__ATOMIC_ACQUIRE, "agent");
;             xb_add(&bar[XB_XGEN(b.x)], 1u);
;             asm volatile("s_waitcnt vmcnt(0)" ::: "memory");
;         } else {
;             XB_SPIN(xb_ld(&bar[XB_XGEN(b.x)]) == gen, bar);
.LBB0_54:
	s_or_b64 exec, exec, s[8:9]
	v_cvt_f32_u32_e32 v4, v2
	s_waitcnt vmcnt(0)
	v_readfirstlane_b32 s0, v3
	v_sub_u32_e32 v3, 0, v2
	v_rcp_iflag_f32_e32 v4, v4
	v_add_u32_e32 v5, s0, v1
	v_mul_f32_e32 v4, 0x4f7ffffe, v4
	v_cvt_u32_f32_e32 v4, v4
	v_mul_lo_u32 v1, v3, v4
	v_mul_hi_u32 v1, v4, v1
	v_add_u32_e32 v1, v4, v1
	v_mul_hi_u32 v1, v5, v1
	v_mul_lo_u32 v3, v1, v2
	v_sub_u32_e32 v3, v5, v3
	v_add_u32_e32 v4, 1, v1
	v_cmp_ge_u32_e32 vcc, v3, v2
	s_nop 1
	v_cndmask_b32_e32 v1, v1, v4, vcc
	v_sub_u32_e32 v4, v3, v2
	v_cndmask_b32_e32 v3, v3, v4, vcc
	v_add_u32_e32 v4, 1, v1
	v_cmp_ge_u32_e32 vcc, v3, v2
	v_add_u32_e32 v3, 1, v5
	s_nop 0
	v_cndmask_b32_e32 v1, v1, v4, vcc
	v_mul_lo_u32 v4, v2, v1
	v_add_u32_e32 v2, v4, v2
	v_cmp_ne_u32_e32 vcc, v3, v2
	s_and_saveexec_b64 s[0:1], vcc
	s_xor_b64 s[0:1], exec, s[0:1]
	s_cbranch_execz .LBB0_68
	s_waitcnt lgkmcnt(0)
	s_add_u32 s12, s84, 0xc13500
	s_addc_u32 s13, s85, 0
	v_mov_b32_e32 v0, 0
	global_load_dword v0, v0, s[12:13] sc1
	s_waitcnt vmcnt(0)
	v_cmp_eq_u32_e32 vcc, v0, v1
	s_and_saveexec_b64 s[8:9], vcc
	s_cbranch_execz .LBB0_67
	s_add_u32 s10, s84, 0xc10200
	s_addc_u32 s11, s85, 0
	s_mov_b32 s3, 1
	s_mov_b64 s[14:15], 0
	v_mov_b32_e32 v0, 0
	s_branch .LBB0_58

; __device__ __forceinline__ unsigned xb_ld(unsigned* p)              { return __hip_atomic_load(p, __ATOMIC_RELAXED, __HIP_MEMORY_SCOPE_AGENT); }
; __device__ __forceinline__ unsigned xb_add(unsigned* p, unsigned v) { return __hip_atomic_fetch_add(p, v, __ATOMIC_RELAXED, __HIP_MEMORY_SCOPE_AGENT); }
; #define XB_SPIN(cond, bar) do { unsigned _sp = 0; while (cond) { __builtin_amdgcn_s_sleep(1); \
;     if ((++_sp & 255u) == 0u) { if (xb_ld(&(bar)[XB_TMO])) break; if (_sp > XB_SPIN_CAP) { atomicAdd(&(bar)[XB_TMO], 1u); break; } } } } while (0)
; __device__ __forceinline__ void xcd_barrier(const XcdBarrier& b) {
;     ...
;             const unsigned og = xb_add(&bar[XB_TOP], 1u);
;             const unsigned tg = og / nx;
;             if (og + 1u == (tg + 1u) * nx) xb_add(&bar[XB_TOPGEN], 1u);
;             else XB_SPIN(xb_ld(&bar[XB_TOPGEN]) == tg, bar);
;             __builtin_amdgcn_fence(__ATOMIC_ACQUIRE, "agent");
;             xb_add(&bar[XB_XGEN(b.x)], 1u);
.LBB0_85:
	s_or_b64 exec, exec, s[0:1]
	s_mov_b64 s[0:1], exec
	v_mbcnt_lo_u32_b32 v0, s0, 0
	v_mbcnt_hi_u32_b32 v0, s1, v0
	v_cmp_eq_u32_e32 vcc, 0, v0
	s_waitcnt vmcnt(0)
	buffer_inv sc1
	s_and_saveexec_b64 s[8:9], vcc
	s_cbranch_execz .LBB0_87
	s_bcnt1_i32_b64 s0, s[0:1]
	v_mov_b32_e32 v0, 0x2000
	v_mov_b32_e32 v1, s0
	s_nop 0

; __device__ __forceinline__ unsigned xb_ld(unsigned* p)              { return __hip_atomic_load(p, __ATOMIC_RELAXED, __HIP_MEMORY_SCOPE_AGENT); }
; __device__ __forceinline__ unsigned xb_add(unsigned* p, unsigned v) { return __hip_atomic_fetch_add(p, v, __ATOMIC_RELAXED, __HIP_MEMORY_SCOPE_AGENT); }
; #define XB_SPIN(cond, bar) do { unsigned _sp = 0; while (cond) { __builtin_amdgcn_s_sleep(1); \
;     if ((++_sp & 255u) == 0u) { if (xb_ld(&(bar)[XB_TMO])) break; if (_sp > XB_SPIN_CAP) { atomicAdd(&(bar)[XB_TMO], 1u); break; } } } } while (0)
; __device__ __forceinline__ void xcd_barrier(const XcdBarrier& b) {
;     ...
;         const unsigned old = xb_add(&bar[XB_XSUB(b.x)], 1u);
;         const unsigned gen = old / nloc;
;         if (old + 1u == (gen + 1u) * nloc) {
;             __builtin_amdgcn_fence(__ATOMIC_RELEASE, "agent");
;             asm volatile("s_waitcnt vmcnt(0)" ::: "memory");
;             const unsigned og = xb_add(&bar[XB_TOP], 1u);
;             const unsigned tg = og / nx;
;             if (og + 1u == (tg + 1u) * nx) xb_add(&bar[XB_TOPGEN], 1u);
;             else XB_SPIN(xb_ld(&bar[XB_TOPGEN]) == tg, bar);
;             __builtin_amdgcn_fence(__ATOMIC_ACQUIRE, "agent");
;             xb_add(&bar[XB_XGEN(b.x)], 1u);
;             asm volatile("s_waitcnt vmcnt(0)" ::: "memory");
;         } else {
;             XB_SPIN(xb_ld(&bar[XB_XGEN(b.x)]) == gen, bar);
.LBB0_494:
	s_or_b64 exec, exec, s[12:13]
	v_cvt_f32_u32_e32 v4, v2
	s_waitcnt vmcnt(0)
	v_readfirstlane_b32 s0, v3
	v_sub_u32_e32 v3, 0, v2
	v_rcp_iflag_f32_e32 v4, v4
	v_add_u32_e32 v5, s0, v1
	v_mul_f32_e32 v4, 0x4f7ffffe, v4
	v_cvt_u32_f32_e32 v4, v4
	v_mul_lo_u32 v1, v3, v4
	v_mul_hi_u32 v1, v4, v1
	v_add_u32_e32 v1, v4, v1
	v_mul_hi_u32 v1, v5, v1
	v_mul_lo_u32 v3, v1, v2
	v_sub_u32_e32 v3, v5, v3
	v_add_u32_e32 v4, 1, v1
	v_cmp_ge_u32_e32 vcc, v3, v2
	s_nop 1
	v_cndmask_b32_e32 v1, v1, v4, vcc
	v_sub_u32_e32 v4, v3, v2
	v_cndmask_b32_e32 v3, v3, v4, vcc
	v_add_u32_e32 v4, 1, v1
	v_cmp_ge_u32_e32 vcc, v3, v2
	v_add_u32_e32 v3, 1, v5
	s_nop 0
	v_cndmask_b32_e32 v1, v1, v4, vcc
	v_mul_lo_u32 v4, v2, v1
	v_add_u32_e32 v2, v4, v2
	v_cmp_ne_u32_e32 vcc, v3, v2
	s_and_saveexec_b64 s[0:1], vcc
	s_xor_b64 s[0:1], exec, s[0:1]
	s_cbranch_execz .LBB0_508
	s_waitcnt lgkmcnt(0)
	s_add_u32 s18, s84, 0xc13500
	s_addc_u32 s19, s85, 0
	v_mov_b32_e32 v0, 0
	global_load_dword v0, v0, s[18:19] sc1
	s_waitcnt vmcnt(0)
	v_cmp_eq_u32_e32 vcc, v0, v1
	s_and_saveexec_b64 s[12:13], vcc
	s_cbranch_execz .LBB0_507
	s_add_u32 s14, s84, 0xc10200
	s_addc_u32 s15, s85, 0
	s_mov_b32 s4, 1
	s_mov_b64 s[44:45], 0
	v_mov_b32_e32 v0, 0
	s_branch .LBB0_498

; __device__ __forceinline__ unsigned xb_ld(unsigned* p)              { return __hip_atomic_load(p, __ATOMIC_RELAXED, __HIP_MEMORY_SCOPE_AGENT); }
; __device__ __forceinline__ unsigned xb_add(unsigned* p, unsigned v) { return __hip_atomic_fetch_add(p, v, __ATOMIC_RELAXED, __HIP_MEMORY_SCOPE_AGENT); }
; #define XB_SPIN(cond, bar) do { unsigned _sp = 0; while (cond) { __builtin_amdgcn_s_sleep(1); \
;     if ((++_sp & 255u) == 0u) { if (xb_ld(&(bar)[XB_TMO])) break; if (_sp > XB_SPIN_CAP) { atomicAdd(&(bar)[XB_TMO], 1u); break; } } } } while (0)
; __device__ __forceinline__ void xcd_barrier(const XcdBarrier& b) {
;     ...
;             const unsigned og = xb_add(&bar[XB_TOP], 1u);
;             const unsigned tg = og / nx;
;             if (og + 1u == (tg + 1u) * nx) xb_add(&bar[XB_TOPGEN], 1u);
;             else XB_SPIN(xb_ld(&bar[XB_TOPGEN]) == tg, bar);
;             __builtin_amdgcn_fence(__ATOMIC_ACQUIRE, "agent");
;             xb_add(&bar[XB_XGEN(b.x)], 1u);
.LBB0_525:
	s_or_b64 exec, exec, s[0:1]
	s_mov_b64 s[0:1], exec
	v_mbcnt_lo_u32_b32 v0, s0, 0
	v_mbcnt_hi_u32_b32 v0, s1, v0
	v_cmp_eq_u32_e32 vcc, 0, v0
	s_waitcnt vmcnt(0)
	buffer_inv sc1
	s_and_saveexec_b64 s[12:13], vcc
	s_cbranch_execz .LBB0_527
	s_bcnt1_i32_b64 s0, s[0:1]
	v_mov_b32_e32 v0, 0x2000
	v_mov_b32_e32 v1, s0
	s_nop 0

; __device__ __forceinline__ unsigned xb_ld(unsigned* p)              { return __hip_atomic_load(p, __ATOMIC_RELAXED, __HIP_MEMORY_SCOPE_AGENT); }
; __device__ __forceinline__ unsigned xb_add(unsigned* p, unsigned v) { return __hip_atomic_fetch_add(p, v, __ATOMIC_RELAXED, __HIP_MEMORY_SCOPE_AGENT); }
; #define XB_SPIN(cond, bar) do { unsigned _sp = 0; while (cond) { __builtin_amdgcn_s_sleep(1); \
;     if ((++_sp & 255u) == 0u) { if (xb_ld(&(bar)[XB_TMO])) break; if (_sp > XB_SPIN_CAP) { atomicAdd(&(bar)[XB_TMO], 1u); break; } } } } while (0)
; __device__ __forceinline__ void xcd_barrier(const XcdBarrier& b) {
;     ...
;         const unsigned old = xb_add(&bar[XB_XSUB(b.x)], 1u);
;         const unsigned gen = old / nloc;
;         if (old + 1u == (gen + 1u) * nloc) {
;             __builtin_amdgcn_fence(__ATOMIC_RELEASE, "agent");
;             asm volatile("s_waitcnt vmcnt(0)" ::: "memory");
;             const unsigned og = xb_add(&bar[XB_TOP], 1u);
;             const unsigned tg = og / nx;
;             if (og + 1u == (tg + 1u) * nx) xb_add(&bar[XB_TOPGEN], 1u);
;             else XB_SPIN(xb_ld(&bar[XB_TOPGEN]) == tg, bar);
;             __builtin_amdgcn_fence(__ATOMIC_ACQUIRE, "agent");
;             xb_add(&bar[XB_XGEN(b.x)], 1u);
;             asm volatile("s_waitcnt vmcnt(0)" ::: "memory");
;         } else {
;             XB_SPIN(xb_ld(&bar[XB_XGEN(b.x)]) == gen, bar);
.LBB0_824:
	s_or_b64 exec, exec, s[10:11]
	v_cvt_f32_u32_e32 v4, v2
	s_waitcnt vmcnt(0)
	v_readfirstlane_b32 s0, v3
	v_sub_u32_e32 v3, 0, v2
	v_rcp_iflag_f32_e32 v4, v4
	v_add_u32_e32 v5, s0, v1
	v_mul_f32_e32 v4, 0x4f7ffffe, v4
	v_cvt_u32_f32_e32 v4, v4
	v_mul_lo_u32 v1, v3, v4
	v_mul_hi_u32 v1, v4, v1
	v_add_u32_e32 v1, v4, v1
	v_mul_hi_u32 v1, v5, v1
	v_mul_lo_u32 v3, v1, v2
	v_sub_u32_e32 v3, v5, v3
	v_add_u32_e32 v4, 1, v1
	v_cmp_ge_u32_e32 vcc, v3, v2
	s_nop 1
	v_cndmask_b32_e32 v1, v1, v4, vcc
	v_sub_u32_e32 v4, v3, v2
	v_cndmask_b32_e32 v3, v3, v4, vcc
	v_add_u32_e32 v4, 1, v1
	v_cmp_ge_u32_e32 vcc, v3, v2
	v_add_u32_e32 v3, 1, v5
	s_nop 0
	v_cndmask_b32_e32 v1, v1, v4, vcc
	v_mul_lo_u32 v4, v2, v1
	v_add_u32_e32 v2, v4, v2
	v_cmp_ne_u32_e32 vcc, v3, v2
	s_and_saveexec_b64 s[0:1], vcc
	s_xor_b64 s[0:1], exec, s[0:1]
	s_cbranch_execz .LBB0_838
	s_waitcnt lgkmcnt(0)
	s_add_u32 s14, s84, 0xc13500
	s_addc_u32 s15, s85, 0
	v_mov_b32_e32 v0, 0
	global_load_dword v0, v0, s[14:15] sc1
	s_waitcnt vmcnt(0)
	v_cmp_eq_u32_e32 vcc, v0, v1
	s_and_saveexec_b64 s[10:11], vcc
	s_cbranch_execz .LBB0_837
	s_add_u32 s12, s84, 0xc10200
	s_addc_u32 s13, s85, 0
	s_mov_b32 s4, 1
	s_mov_b64 s[18:19], 0
	v_mov_b32_e32 v0, 0
	s_branch .LBB0_828

; __device__ __forceinline__ unsigned xb_ld(unsigned* p)              { return __hip_atomic_load(p, __ATOMIC_RELAXED, __HIP_MEMORY_SCOPE_AGENT); }
; __device__ __forceinline__ unsigned xb_add(unsigned* p, unsigned v) { return __hip_atomic_fetch_add(p, v, __ATOMIC_RELAXED, __HIP_MEMORY_SCOPE_AGENT); }
; #define XB_SPIN(cond, bar) do { unsigned _sp = 0; while (cond) { __builtin_amdgcn_s_sleep(1); \
;     if ((++_sp & 255u) == 0u) { if (xb_ld(&(bar)[XB_TMO])) break; if (_sp > XB_SPIN_CAP) { atomicAdd(&(bar)[XB_TMO], 1u); break; } } } } while (0)
; __device__ __forceinline__ void xcd_barrier(const XcdBarrier& b) {
;     ...
;             if (og + 1u == (tg + 1u) * nx) xb_add(&bar[XB_TOPGEN], 1u);
;             else XB_SPIN(xb_ld(&bar[XB_TOPGEN]) == tg, bar);
;             __builtin_amdgcn_fence(__ATOMIC_ACQUIRE, "agent");
;             xb_add(&bar[XB_XGEN(b.x)], 1u);
;             asm volatile("s_waitcnt vmcnt(0)" ::: "memory");
.LBB0_855:
	s_or_b64 exec, exec, s[0:1]
	s_mov_b64 s[0:1], exec
	v_mbcnt_lo_u32_b32 v0, s0, 0
	v_mbcnt_hi_u32_b32 v0, s1, v0
	v_cmp_eq_u32_e32 vcc, 0, v0
	s_waitcnt vmcnt(0)
	buffer_inv sc1
	s_and_saveexec_b64 s[10:11], vcc
	s_cbranch_execz .LBB0_857
	s_bcnt1_i32_b64 s0, s[0:1]
	v_mov_b32_e32 v0, 0x2000
	v_mov_b32_e32 v1, s0
	s_nop 0

; __device__ __forceinline__ unsigned xb_ld(unsigned* p)              { return __hip_atomic_load(p, __ATOMIC_RELAXED, __HIP_MEMORY_SCOPE_AGENT); }
; __device__ __forceinline__ unsigned xb_add(unsigned* p, unsigned v) { return __hip_atomic_fetch_add(p, v, __ATOMIC_RELAXED, __HIP_MEMORY_SCOPE_AGENT); }
; #define XB_SPIN(cond, bar) do { unsigned _sp = 0; while (cond) { __builtin_amdgcn_s_sleep(1); \
;     if ((++_sp & 255u) == 0u) { if (xb_ld(&(bar)[XB_TMO])) break; if (_sp > XB_SPIN_CAP) { atomicAdd(&(bar)[XB_TMO], 1u); break; } } } } while (0)
; __device__ __forceinline__ void xcd_barrier(const XcdBarrier& b) {
;     ...
;         const unsigned old = xb_add(&bar[XB_XSUB(b.x)], 1u);
;         const unsigned gen = old / nloc;
;         if (old + 1u == (gen + 1u) * nloc) {
;             __builtin_amdgcn_fence(__ATOMIC_RELEASE, "agent");
;             asm volatile("s_waitcnt vmcnt(0)" ::: "memory");
;             const unsigned og = xb_add(&bar[XB_TOP], 1u);
;             const unsigned tg = og / nx;
;             if (og + 1u == (tg + 1u) * nx) xb_add(&bar[XB_TOPGEN], 1u);
;             else XB_SPIN(xb_ld(&bar[XB_TOPGEN]) == tg, bar);
;             __builtin_amdgcn_fence(__ATOMIC_ACQUIRE, "agent");
;             xb_add(&bar[XB_XGEN(b.x)], 1u);
;             asm volatile("s_waitcnt vmcnt(0)" ::: "memory");
;         } else {
;             XB_SPIN(xb_ld(&bar[XB_XGEN(b.x)]) == gen, bar);
.LBB0_898:
	s_or_b64 exec, exec, s[8:9]
	v_cvt_f32_u32_e32 v4, v2
	s_waitcnt vmcnt(0)
	v_readfirstlane_b32 s0, v3
	v_sub_u32_e32 v3, 0, v2
	v_rcp_iflag_f32_e32 v4, v4
	v_add_u32_e32 v5, s0, v1
	v_mul_f32_e32 v4, 0x4f7ffffe, v4
	v_cvt_u32_f32_e32 v4, v4
	v_mul_lo_u32 v1, v3, v4
	v_mul_hi_u32 v1, v4, v1
	v_add_u32_e32 v1, v4, v1
	v_mul_hi_u32 v1, v5, v1
	v_mul_lo_u32 v3, v1, v2
	v_sub_u32_e32 v3, v5, v3
	v_add_u32_e32 v4, 1, v1
	v_cmp_ge_u32_e32 vcc, v3, v2
	s_nop 1
	v_cndmask_b32_e32 v1, v1, v4, vcc
	v_sub_u32_e32 v4, v3, v2
	v_cndmask_b32_e32 v3, v3, v4, vcc
	v_add_u32_e32 v4, 1, v1
	v_cmp_ge_u32_e32 vcc, v3, v2
	v_add_u32_e32 v3, 1, v5
	s_nop 0
	v_cndmask_b32_e32 v1, v1, v4, vcc
	v_mul_lo_u32 v4, v2, v1
	v_add_u32_e32 v2, v4, v2
	v_cmp_ne_u32_e32 vcc, v3, v2
	s_and_saveexec_b64 s[0:1], vcc
	s_xor_b64 s[0:1], exec, s[0:1]
	s_cbranch_execz .LBB0_912
	s_waitcnt lgkmcnt(0)
	s_add_u32 s12, s84, 0xc13500
	s_addc_u32 s13, s85, 0
	v_mov_b32_e32 v0, 0
	global_load_dword v0, v0, s[12:13] sc1
	s_waitcnt vmcnt(0)
	v_cmp_eq_u32_e32 vcc, v0, v1
	s_and_saveexec_b64 s[8:9], vcc
	s_cbranch_execz .LBB0_911
	s_add_u32 s10, s84, 0xc10200
	s_addc_u32 s11, s85, 0
	s_mov_b32 s16, 1
	s_mov_b64 s[14:15], 0
	v_mov_b32_e32 v0, 0
	s_branch .LBB0_902

; __device__ __forceinline__ unsigned xb_ld(unsigned* p)              { return __hip_atomic_load(p, __ATOMIC_RELAXED, __HIP_MEMORY_SCOPE_AGENT); }
; __device__ __forceinline__ unsigned xb_add(unsigned* p, unsigned v) { return __hip_atomic_fetch_add(p, v, __ATOMIC_RELAXED, __HIP_MEMORY_SCOPE_AGENT); }
; #define XB_SPIN(cond, bar) do { unsigned _sp = 0; while (cond) { __builtin_amdgcn_s_sleep(1); \
;     if ((++_sp & 255u) == 0u) { if (xb_ld(&(bar)[XB_TMO])) break; if (_sp > XB_SPIN_CAP) { atomicAdd(&(bar)[XB_TMO], 1u); break; } } } } while (0)
; __device__ __forceinline__ void xcd_barrier(const XcdBarrier& b) {
;     ...
;         const unsigned old = xb_add(&bar[XB_XSUB(b.x)], 1u);
;         const unsigned gen = old / nloc;
;         if (old + 1u == (gen + 1u) * nloc) {
;             __builtin_amdgcn_fence(__ATOMIC_RELEASE, "agent");
;             asm volatile("s_waitcnt vmcnt(0)" ::: "memory");
;             const unsigned og = xb_add(&bar[XB_TOP], 1u);
;             const unsigned tg = og / nx;
;             if (og + 1u == (tg + 1u) * nx) xb_add(&bar[XB_TOPGEN], 1u);
;             else XB_SPIN(xb_ld(&bar[XB_TOPGEN]) == tg, bar);
;             __builtin_amdgcn_fence(__ATOMIC_ACQUIRE, "agent");
;             xb_add(&bar[XB_XGEN(b.x)], 1u);
;             asm volatile("s_waitcnt vmcnt(0)" ::: "memory");
;         } else {
;             XB_SPIN(xb_ld(&bar[XB_XGEN(b.x)]) == gen, bar);
.LBB0_1004:
	s_or_b64 exec, exec, s[12:13]
	v_cvt_f32_u32_e32 v4, v2
	s_waitcnt vmcnt(0)
	v_readfirstlane_b32 s0, v3
	v_sub_u32_e32 v3, 0, v2
	v_rcp_iflag_f32_e32 v4, v4
	v_add_u32_e32 v5, s0, v1
	v_mul_f32_e32 v4, 0x4f7ffffe, v4
	v_cvt_u32_f32_e32 v4, v4
	v_mul_lo_u32 v1, v3, v4
	v_mul_hi_u32 v1, v4, v1
	v_add_u32_e32 v1, v4, v1
	v_mul_hi_u32 v1, v5, v1
	v_mul_lo_u32 v3, v1, v2
	v_sub_u32_e32 v3, v5, v3
	v_add_u32_e32 v4, 1, v1
	v_cmp_ge_u32_e32 vcc, v3, v2
	s_nop 1
	v_cndmask_b32_e32 v1, v1, v4, vcc
	v_sub_u32_e32 v4, v3, v2
	v_cndmask_b32_e32 v3, v3, v4, vcc
	v_add_u32_e32 v4, 1, v1
	v_cmp_ge_u32_e32 vcc, v3, v2
	v_add_u32_e32 v3, 1, v5
	s_nop 0
	v_cndmask_b32_e32 v1, v1, v4, vcc
	v_mul_lo_u32 v4, v2, v1
	v_add_u32_e32 v2, v4, v2
	v_cmp_ne_u32_e32 vcc, v3, v2
	s_and_saveexec_b64 s[0:1], vcc
	s_xor_b64 s[0:1], exec, s[0:1]
	s_cbranch_execz .LBB0_1018
	s_waitcnt lgkmcnt(0)
	s_add_u32 s18, s84, 0xc13500
	s_addc_u32 s19, s85, 0
	v_mov_b32_e32 v0, 0
	global_load_dword v0, v0, s[18:19] sc1
	s_waitcnt vmcnt(0)
	v_cmp_eq_u32_e32 vcc, v0, v1
	s_and_saveexec_b64 s[12:13], vcc
	s_cbranch_execz .LBB0_1017
	s_add_u32 s14, s84, 0xc10200
	s_addc_u32 s15, s85, 0
	s_mov_b32 s4, 1
	s_mov_b64 s[46:47], 0
	v_mov_b32_e32 v0, 0
	s_branch .LBB0_1008

; __device__ __forceinline__ unsigned xb_ld(unsigned* p)              { return __hip_atomic_load(p, __ATOMIC_RELAXED, __HIP_MEMORY_SCOPE_AGENT); }
; __device__ __forceinline__ unsigned xb_add(unsigned* p, unsigned v) { return __hip_atomic_fetch_add(p, v, __ATOMIC_RELAXED, __HIP_MEMORY_SCOPE_AGENT); }
; #define XB_SPIN(cond, bar) do { unsigned _sp = 0; while (cond) { __builtin_amdgcn_s_sleep(1); \
;     if ((++_sp & 255u) == 0u) { if (xb_ld(&(bar)[XB_TMO])) break; if (_sp > XB_SPIN_CAP) { atomicAdd(&(bar)[XB_TMO], 1u); break; } } } } while (0)
; __device__ __forceinline__ void xcd_barrier(const XcdBarrier& b) {
;     ...
;         const unsigned old = xb_add(&bar[XB_XSUB(b.x)], 1u);
;         const unsigned gen = old / nloc;
;         if (old + 1u == (gen + 1u) * nloc) {
;             __builtin_amdgcn_fence(__ATOMIC_RELEASE, "agent");
;             asm volatile("s_waitcnt vmcnt(0)" ::: "memory");
;             const unsigned og = xb_add(&bar[XB_TOP], 1u);
;             const unsigned tg = og / nx;
;             if (og + 1u == (tg + 1u) * nx) xb_add(&bar[XB_TOPGEN], 1u);
;             else XB_SPIN(xb_ld(&bar[XB_TOPGEN]) == tg, bar);
;             __builtin_amdgcn_fence(__ATOMIC_ACQUIRE, "agent");
;             xb_add(&bar[XB_XGEN(b.x)], 1u);
;             asm volatile("s_waitcnt vmcnt(0)" ::: "memory");
;         } else {
;             XB_SPIN(xb_ld(&bar[XB_XGEN(b.x)]) == gen, bar);
.LBB0_1076:
	s_or_b64 exec, exec, s[14:15]
	v_cvt_f32_u32_e32 v4, v2
	s_waitcnt vmcnt(0)
	v_readfirstlane_b32 s0, v3
	v_sub_u32_e32 v3, 0, v2
	v_rcp_iflag_f32_e32 v4, v4
	v_add_u32_e32 v5, s0, v1
	v_mul_f32_e32 v4, 0x4f7ffffe, v4
	v_cvt_u32_f32_e32 v4, v4
	v_mul_lo_u32 v1, v3, v4
	v_mul_hi_u32 v1, v4, v1
	v_add_u32_e32 v1, v4, v1
	v_mul_hi_u32 v1, v5, v1
	v_mul_lo_u32 v3, v1, v2
	v_sub_u32_e32 v3, v5, v3
	v_add_u32_e32 v4, 1, v1
	v_cmp_ge_u32_e32 vcc, v3, v2
	s_nop 1
	v_cndmask_b32_e32 v1, v1, v4, vcc
	v_sub_u32_e32 v4, v3, v2
	v_cndmask_b32_e32 v3, v3, v4, vcc
	v_add_u32_e32 v4, 1, v1
	v_cmp_ge_u32_e32 vcc, v3, v2
	v_add_u32_e32 v3, 1, v5
	s_nop 0
	v_cndmask_b32_e32 v1, v1, v4, vcc
	v_mul_lo_u32 v4, v2, v1
	v_add_u32_e32 v2, v4, v2
	v_cmp_ne_u32_e32 vcc, v3, v2
	s_and_saveexec_b64 s[0:1], vcc
	s_xor_b64 s[0:1], exec, s[0:1]
	s_cbranch_execz .LBB0_1090
	s_waitcnt lgkmcnt(0)
	s_add_u32 s46, s84, 0xc13500
	s_addc_u32 s47, s85, 0
	v_mov_b32_e32 v0, 0
	global_load_dword v0, v0, s[46:47] sc1
	s_waitcnt vmcnt(0)
	v_cmp_eq_u32_e32 vcc, v0, v1
	s_and_saveexec_b64 s[14:15], vcc
	s_cbranch_execz .LBB0_1089
	s_add_u32 s18, s84, 0xc10200
	s_addc_u32 s19, s85, 0
	s_mov_b32 s4, 1
	s_mov_b64 s[48:49], 0
	v_mov_b32_e32 v0, 0
	s_branch .LBB0_1080

; __device__ __forceinline__ unsigned xb_ld(unsigned* p)              { return __hip_atomic_load(p, __ATOMIC_RELAXED, __HIP_MEMORY_SCOPE_AGENT); }
; __device__ __forceinline__ unsigned xb_add(unsigned* p, unsigned v) { return __hip_atomic_fetch_add(p, v, __ATOMIC_RELAXED, __HIP_MEMORY_SCOPE_AGENT); }
; #define XB_SPIN(cond, bar) do { unsigned _sp = 0; while (cond) { __builtin_amdgcn_s_sleep(1); \
;     if ((++_sp & 255u) == 0u) { if (xb_ld(&(bar)[XB_TMO])) break; if (_sp > XB_SPIN_CAP) { atomicAdd(&(bar)[XB_TMO], 1u); break; } } } } while (0)
; __device__ __forceinline__ void xcd_barrier(const XcdBarrier& b) {
;     ...
;             if (og + 1u == (tg + 1u) * nx) xb_add(&bar[XB_TOPGEN], 1u);
;             else XB_SPIN(xb_ld(&bar[XB_TOPGEN]) == tg, bar);
;             __builtin_amdgcn_fence(__ATOMIC_ACQUIRE, "agent");
;             xb_add(&bar[XB_XGEN(b.x)], 1u);
;             asm volatile("s_waitcnt vmcnt(0)" ::: "memory");
.LBB0_1107:
	s_or_b64 exec, exec, s[0:1]
	s_mov_b64 s[0:1], exec
	v_mbcnt_lo_u32_b32 v0, s0, 0
	v_mbcnt_hi_u32_b32 v0, s1, v0
	v_cmp_eq_u32_e32 vcc, 0, v0
	s_waitcnt vmcnt(0)
	buffer_inv sc1
	s_and_saveexec_b64 s[14:15], vcc
	s_cbranch_execz .LBB0_1109
	s_bcnt1_i32_b64 s0, s[0:1]
	v_mov_b32_e32 v0, 0x2000
	v_mov_b32_e32 v1, s0
	s_nop 0

; __device__ __forceinline__ unsigned xb_ld(unsigned* p)              { return __hip_atomic_load(p, __ATOMIC_RELAXED, __HIP_MEMORY_SCOPE_AGENT); }
; __device__ __forceinline__ unsigned xb_add(unsigned* p, unsigned v) { return __hip_atomic_fetch_add(p, v, __ATOMIC_RELAXED, __HIP_MEMORY_SCOPE_AGENT); }
; #define XB_SPIN(cond, bar) do { unsigned _sp = 0; while (cond) { __builtin_amdgcn_s_sleep(1); \
;     if ((++_sp & 255u) == 0u) { if (xb_ld(&(bar)[XB_TMO])) break; if (_sp > XB_SPIN_CAP) { atomicAdd(&(bar)[XB_TMO], 1u); break; } } } } while (0)
; __device__ __forceinline__ void xcd_barrier(const XcdBarrier& b) {
;     ...
;         const unsigned old = xb_add(&bar[XB_XSUB(b.x)], 1u);
;         const unsigned gen = old / nloc;
;         if (old + 1u == (gen + 1u) * nloc) {
;             __builtin_amdgcn_fence(__ATOMIC_RELEASE, "agent");
;             asm volatile("s_waitcnt vmcnt(0)" ::: "memory");
;             const unsigned og = xb_add(&bar[XB_TOP], 1u);
;             const unsigned tg = og / nx;
;             if (og + 1u == (tg + 1u) * nx) xb_add(&bar[XB_TOPGEN], 1u);
;             else XB_SPIN(xb_ld(&bar[XB_TOPGEN]) == tg, bar);
;             __builtin_amdgcn_fence(__ATOMIC_ACQUIRE, "agent");
;             xb_add(&bar[XB_XGEN(b.x)], 1u);
;             asm volatile("s_waitcnt vmcnt(0)" ::: "memory");
;         } else {
;             XB_SPIN(xb_ld(&bar[XB_XGEN(b.x)]) == gen, bar);
.LBB0_1158:
	s_or_b64 exec, exec, s[12:13]
	v_cvt_f32_u32_e32 v4, v2
	s_waitcnt vmcnt(0)
	v_readfirstlane_b32 s0, v3
	v_sub_u32_e32 v3, 0, v2
	v_rcp_iflag_f32_e32 v4, v4
	v_add_u32_e32 v5, s0, v1
	v_mul_f32_e32 v4, 0x4f7ffffe, v4
	v_cvt_u32_f32_e32 v4, v4
	v_mul_lo_u32 v1, v3, v4
	v_mul_hi_u32 v1, v4, v1
	v_add_u32_e32 v1, v4, v1
	v_mul_hi_u32 v1, v5, v1
	v_mul_lo_u32 v3, v1, v2
	v_sub_u32_e32 v3, v5, v3
	v_add_u32_e32 v4, 1, v1
	v_cmp_ge_u32_e32 vcc, v3, v2
	s_nop 1
	v_cndmask_b32_e32 v1, v1, v4, vcc
	v_sub_u32_e32 v4, v3, v2
	v_cndmask_b32_e32 v3, v3, v4, vcc
	v_add_u32_e32 v4, 1, v1
	v_cmp_ge_u32_e32 vcc, v3, v2
	v_add_u32_e32 v3, 1, v5
	s_nop 0
	v_cndmask_b32_e32 v1, v1, v4, vcc
	v_mul_lo_u32 v4, v2, v1
	v_add_u32_e32 v2, v4, v2
	v_cmp_ne_u32_e32 vcc, v3, v2
	s_and_saveexec_b64 s[0:1], vcc
	s_xor_b64 s[0:1], exec, s[0:1]
	s_cbranch_execz .LBB0_1172
	s_waitcnt lgkmcnt(0)
	s_add_u32 s18, s84, 0xc13500
	s_addc_u32 s19, s85, 0
	v_mov_b32_e32 v0, 0
	global_load_dword v0, v0, s[18:19] sc1
	s_waitcnt vmcnt(0)
	v_cmp_eq_u32_e32 vcc, v0, v1
	s_and_saveexec_b64 s[12:13], vcc
	s_cbranch_execz .LBB0_1171
	s_add_u32 s14, s84, 0xc10200
	s_addc_u32 s15, s85, 0
	s_mov_b32 s4, 1
	s_mov_b64 s[36:37], 0
	v_mov_b32_e32 v0, 0
	s_branch .LBB0_1162

; __device__ __forceinline__ unsigned xb_ld(unsigned* p)              { return __hip_atomic_load(p, __ATOMIC_RELAXED, __HIP_MEMORY_SCOPE_AGENT); }
; __device__ __forceinline__ unsigned xb_add(unsigned* p, unsigned v) { return __hip_atomic_fetch_add(p, v, __ATOMIC_RELAXED, __HIP_MEMORY_SCOPE_AGENT); }
; #define XB_SPIN(cond, bar) do { unsigned _sp = 0; while (cond) { __builtin_amdgcn_s_sleep(1); \
;     if ((++_sp & 255u) == 0u) { if (xb_ld(&(bar)[XB_TMO])) break; if (_sp > XB_SPIN_CAP) { atomicAdd(&(bar)[XB_TMO], 1u); break; } } } } while (0)
; __device__ __forceinline__ void xcd_barrier(const XcdBarrier& b) {
;     ...
;         const unsigned old = xb_add(&bar[XB_XSUB(b.x)], 1u);
;         const unsigned gen = old / nloc;
;         if (old + 1u == (gen + 1u) * nloc) {
;             __builtin_amdgcn_fence(__ATOMIC_RELEASE, "agent");
;             asm volatile("s_waitcnt vmcnt(0)" ::: "memory");
;             const unsigned og = xb_add(&bar[XB_TOP], 1u);
;             const unsigned tg = og / nx;
;             if (og + 1u == (tg + 1u) * nx) xb_add(&bar[XB_TOPGEN], 1u);
;             else XB_SPIN(xb_ld(&bar[XB_TOPGEN]) == tg, bar);
;             __builtin_amdgcn_fence(__ATOMIC_ACQUIRE, "agent");
;             xb_add(&bar[XB_XGEN(b.x)], 1u);
;             asm volatile("s_waitcnt vmcnt(0)" ::: "memory");
;         } else {
;             XB_SPIN(xb_ld(&bar[XB_XGEN(b.x)]) == gen, bar);
.LBB0_1255:
	s_or_b64 exec, exec, s[10:11]
	v_cvt_f32_u32_e32 v4, v2
	s_waitcnt vmcnt(0)
	v_readfirstlane_b32 s0, v3
	v_sub_u32_e32 v3, 0, v2
	v_rcp_iflag_f32_e32 v4, v4
	v_add_u32_e32 v5, s0, v1
	v_mul_f32_e32 v4, 0x4f7ffffe, v4
	v_cvt_u32_f32_e32 v4, v4
	v_mul_lo_u32 v1, v3, v4
	v_mul_hi_u32 v1, v4, v1
	v_add_u32_e32 v1, v4, v1
	v_mul_hi_u32 v1, v5, v1
	v_mul_lo_u32 v3, v1, v2
	v_sub_u32_e32 v3, v5, v3
	v_add_u32_e32 v4, 1, v1
	v_cmp_ge_u32_e32 vcc, v3, v2
	s_nop 1
	v_cndmask_b32_e32 v1, v1, v4, vcc
	v_sub_u32_e32 v4, v3, v2
	v_cndmask_b32_e32 v3, v3, v4, vcc
	v_add_u32_e32 v4, 1, v1
	v_cmp_ge_u32_e32 vcc, v3, v2
	v_add_u32_e32 v3, 1, v5
	s_nop 0
	v_cndmask_b32_e32 v1, v1, v4, vcc
	v_mul_lo_u32 v4, v2, v1
	v_add_u32_e32 v2, v4, v2
	v_cmp_ne_u32_e32 vcc, v3, v2
	s_and_saveexec_b64 s[0:1], vcc
	s_xor_b64 s[0:1], exec, s[0:1]
	s_cbranch_execz .LBB0_1269
	s_waitcnt lgkmcnt(0)
	s_add_u32 s14, s84, 0xc13500
	s_addc_u32 s15, s85, 0
	v_mov_b32_e32 v0, 0
	global_load_dword v0, v0, s[14:15] sc1
	s_waitcnt vmcnt(0)
	v_cmp_eq_u32_e32 vcc, v0, v1
	s_and_saveexec_b64 s[10:11], vcc
	s_cbranch_execz .LBB0_1268
	s_add_u32 s12, s84, 0xc10200
	s_addc_u32 s13, s85, 0
	s_mov_b32 s4, 1
	s_mov_b64 s[22:23], 0
	v_mov_b32_e32 v0, 0
	s_branch .LBB0_1259

; __device__ __forceinline__ unsigned xb_ld(unsigned* p)              { return __hip_atomic_load(p, __ATOMIC_RELAXED, __HIP_MEMORY_SCOPE_AGENT); }
; __device__ __forceinline__ unsigned xb_add(unsigned* p, unsigned v) { return __hip_atomic_fetch_add(p, v, __ATOMIC_RELAXED, __HIP_MEMORY_SCOPE_AGENT); }
; #define XB_SPIN(cond, bar) do { unsigned _sp = 0; while (cond) { __builtin_amdgcn_s_sleep(1); \
;     if ((++_sp & 255u) == 0u) { if (xb_ld(&(bar)[XB_TMO])) break; if (_sp > XB_SPIN_CAP) { atomicAdd(&(bar)[XB_TMO], 1u); break; } } } } while (0)
; __device__ __forceinline__ void xcd_barrier(const XcdBarrier& b) {
;     ...
;         const unsigned old = xb_add(&bar[XB_XSUB(b.x)], 1u);
;         const unsigned gen = old / nloc;
;         if (old + 1u == (gen + 1u) * nloc) {
;             __builtin_amdgcn_fence(__ATOMIC_RELEASE, "agent");
;             asm volatile("s_waitcnt vmcnt(0)" ::: "memory");
;             const unsigned og = xb_add(&bar[XB_TOP], 1u);
;             const unsigned tg = og / nx;
;             if (og + 1u == (tg + 1u) * nx) xb_add(&bar[XB_TOPGEN], 1u);
;             else XB_SPIN(xb_ld(&bar[XB_TOPGEN]) == tg, bar);
;             __builtin_amdgcn_fence(__ATOMIC_ACQUIRE, "agent");
;             xb_add(&bar[XB_XGEN(b.x)], 1u);
;             asm volatile("s_waitcnt vmcnt(0)" ::: "memory");
;         } else {
;             XB_SPIN(xb_ld(&bar[XB_XGEN(b.x)]) == gen, bar);
.LBB0_1336:
	s_or_b64 exec, exec, s[10:11]
	v_cvt_f32_u32_e32 v4, v2
	s_waitcnt vmcnt(0)
	v_readfirstlane_b32 s0, v3
	v_sub_u32_e32 v3, 0, v2
	v_rcp_iflag_f32_e32 v4, v4
	v_add_u32_e32 v5, s0, v1
	v_mul_f32_e32 v4, 0x4f7ffffe, v4
	v_cvt_u32_f32_e32 v4, v4
	v_mul_lo_u32 v1, v3, v4
	v_mul_hi_u32 v1, v4, v1
	v_add_u32_e32 v1, v4, v1
	v_mul_hi_u32 v1, v5, v1
	v_mul_lo_u32 v3, v1, v2
	v_sub_u32_e32 v3, v5, v3
	v_add_u32_e32 v4, 1, v1
	v_cmp_ge_u32_e32 vcc, v3, v2
	s_nop 1
	v_cndmask_b32_e32 v1, v1, v4, vcc
	v_sub_u32_e32 v4, v3, v2
	v_cndmask_b32_e32 v3, v3, v4, vcc
	v_add_u32_e32 v4, 1, v1
	v_cmp_ge_u32_e32 vcc, v3, v2
	v_add_u32_e32 v3, 1, v5
	s_nop 0
	v_cndmask_b32_e32 v1, v1, v4, vcc
	v_mul_lo_u32 v4, v2, v1
	v_add_u32_e32 v2, v4, v2
	v_cmp_ne_u32_e32 vcc, v3, v2
	s_and_saveexec_b64 s[0:1], vcc
	s_xor_b64 s[0:1], exec, s[0:1]
	s_cbranch_execz .LBB0_1350
	s_waitcnt lgkmcnt(0)
	s_add_u32 s14, s84, 0xc13500
	s_addc_u32 s15, s85, 0
	v_mov_b32_e32 v0, 0
	global_load_dword v0, v0, s[14:15] sc1
	s_waitcnt vmcnt(0)
	v_cmp_eq_u32_e32 vcc, v0, v1
	s_and_saveexec_b64 s[10:11], vcc
	s_cbranch_execz .LBB0_1349
	s_add_u32 s12, s84, 0xc10200
	s_addc_u32 s13, s85, 0
	s_mov_b32 s3, 1
	s_mov_b64 s[18:19], 0
	v_mov_b32_e32 v0, 0
	s_branch .LBB0_1340

; __device__ __forceinline__ unsigned xb_ld(unsigned* p)              { return __hip_atomic_load(p, __ATOMIC_RELAXED, __HIP_MEMORY_SCOPE_AGENT); }
; __device__ __forceinline__ unsigned xb_add(unsigned* p, unsigned v) { return __hip_atomic_fetch_add(p, v, __ATOMIC_RELAXED, __HIP_MEMORY_SCOPE_AGENT); }
; #define XB_SPIN(cond, bar) do { unsigned _sp = 0; while (cond) { __builtin_amdgcn_s_sleep(1); \
;     if ((++_sp & 255u) == 0u) { if (xb_ld(&(bar)[XB_TMO])) break; if (_sp > XB_SPIN_CAP) { atomicAdd(&(bar)[XB_TMO], 1u); break; } } } } while (0)
; __device__ __forceinline__ void xcd_barrier(const XcdBarrier& b) {
;     ...
;         const unsigned old = xb_add(&bar[XB_XSUB(b.x)], 1u);
;         const unsigned gen = old / nloc;
;         if (old + 1u == (gen + 1u) * nloc) {
;             __builtin_amdgcn_fence(__ATOMIC_RELEASE, "agent");
;             asm volatile("s_waitcnt vmcnt(0)" ::: "memory");
;             const unsigned og = xb_add(&bar[XB_TOP], 1u);
;             const unsigned tg = og / nx;
;             if (og + 1u == (tg + 1u) * nx) xb_add(&bar[XB_TOPGEN], 1u);
;             else XB_SPIN(xb_ld(&bar[XB_TOPGEN]) == tg, bar);
;             __builtin_amdgcn_fence(__ATOMIC_ACQUIRE, "agent");
;             xb_add(&bar[XB_XGEN(b.x)], 1u);
;             asm volatile("s_waitcnt vmcnt(0)" ::: "memory");
;         } else {
;             XB_SPIN(xb_ld(&bar[XB_XGEN(b.x)]) == gen, bar);
.LBB0_1408:
	s_or_b64 exec, exec, s[8:9]
	v_cvt_f32_u32_e32 v4, v2
	s_waitcnt vmcnt(0)
	v_readfirstlane_b32 s4, v3
	v_sub_u32_e32 v3, 0, v2
	v_rcp_iflag_f32_e32 v4, v4
	v_add_u32_e32 v5, s4, v1
	v_mul_f32_e32 v4, 0x4f7ffffe, v4
	v_cvt_u32_f32_e32 v4, v4
	v_mul_lo_u32 v1, v3, v4
	v_mul_hi_u32 v1, v4, v1
	v_add_u32_e32 v1, v4, v1
	v_mul_hi_u32 v1, v5, v1
	v_mul_lo_u32 v3, v1, v2
	v_sub_u32_e32 v3, v5, v3
	v_add_u32_e32 v4, 1, v1
	v_cmp_ge_u32_e32 vcc, v3, v2
	s_nop 1
	v_cndmask_b32_e32 v1, v1, v4, vcc
	v_sub_u32_e32 v4, v3, v2
	v_cndmask_b32_e32 v3, v3, v4, vcc
	v_add_u32_e32 v4, 1, v1
	v_cmp_ge_u32_e32 vcc, v3, v2
	v_add_u32_e32 v3, 1, v5
	s_nop 0
	v_cndmask_b32_e32 v1, v1, v4, vcc
	v_mul_lo_u32 v4, v2, v1
	v_add_u32_e32 v2, v4, v2
	v_cmp_ne_u32_e32 vcc, v3, v2
	s_and_saveexec_b64 s[4:5], vcc
	s_xor_b64 s[4:5], exec, s[4:5]
	s_cbranch_execz .LBB0_1422
	s_waitcnt lgkmcnt(0)
	s_add_u32 s12, s84, 0xc13500
	s_addc_u32 s13, s85, 0
	v_mov_b32_e32 v0, 0
	global_load_dword v0, v0, s[12:13] sc1
	s_waitcnt vmcnt(0)
	v_cmp_eq_u32_e32 vcc, v0, v1
	s_and_saveexec_b64 s[8:9], vcc
	s_cbranch_execz .LBB0_1421
	s_add_u32 s10, s84, 0xc10200
	s_addc_u32 s11, s85, 0
	s_mov_b32 s16, 1
	s_mov_b64 s[14:15], 0
	v_mov_b32_e32 v0, 0
	s_branch .LBB0_1412

; __device__ __forceinline__ unsigned xb_ld(unsigned* p)              { return __hip_atomic_load(p, __ATOMIC_RELAXED, __HIP_MEMORY_SCOPE_AGENT); }
; __device__ __forceinline__ unsigned xb_add(unsigned* p, unsigned v) { return __hip_atomic_fetch_add(p, v, __ATOMIC_RELAXED, __HIP_MEMORY_SCOPE_AGENT); }
; #define XB_SPIN(cond, bar) do { unsigned _sp = 0; while (cond) { __builtin_amdgcn_s_sleep(1); \
;     if ((++_sp & 255u) == 0u) { if (xb_ld(&(bar)[XB_TMO])) break; if (_sp > XB_SPIN_CAP) { atomicAdd(&(bar)[XB_TMO], 1u); break; } } } } while (0)
; __device__ __forceinline__ void xcd_barrier(const XcdBarrier& b) {
;     ...
;             if (og + 1u == (tg + 1u) * nx) xb_add(&bar[XB_TOPGEN], 1u);
;             else XB_SPIN(xb_ld(&bar[XB_TOPGEN]) == tg, bar);
;             __builtin_amdgcn_fence(__ATOMIC_ACQUIRE, "agent");
;             xb_add(&bar[XB_XGEN(b.x)], 1u);
;             asm volatile("s_waitcnt vmcnt(0)" ::: "memory");
.LBB0_1439:
	s_or_b64 exec, exec, s[4:5]
	s_mov_b64 s[4:5], exec
	v_mbcnt_lo_u32_b32 v0, s4, 0
	v_mbcnt_hi_u32_b32 v0, s5, v0
	v_cmp_eq_u32_e32 vcc, 0, v0
	s_waitcnt vmcnt(0)
	buffer_inv sc1
	s_and_saveexec_b64 s[8:9], vcc
	s_cbranch_execz .LBB0_1441
	s_bcnt1_i32_b64 s4, s[4:5]
	v_mov_b32_e32 v0, 0x2000
	v_mov_b32_e32 v1, s4
	s_nop 0
